# speedup vs baseline: 1.0051x; 1.0051x over previous
.LBB0_166:
	flat_load_dword v47, v[0:1] sc1
	flat_load_dword v32, v[2:3] sc1
	flat_load_dword v33, v[4:5] sc1
	flat_load_dword v34, v[6:7] sc1
	flat_load_dword v35, v[8:9] sc1
	flat_load_dword v36, v[10:11] sc1
	flat_load_dword v37, v[12:13] sc1
	flat_load_dword v38, v[14:15] sc1
	flat_load_dword v39, v[16:17] sc1
	flat_load_dword v40, v[18:19] sc1
	flat_load_dword v41, v[20:21] sc1
	flat_load_dword v42, v[22:23] sc1
	flat_load_dword v43, v[24:25] sc1
	flat_load_dword v44, v[26:27] sc1
	flat_load_dword v45, v[28:29] sc1
	flat_load_dword v46, v[30:31] sc1
	s_or_b64 s[12:13], s[12:13], exec
	s_or_b64 s[10:11], s[10:11], exec
	s_waitcnt vmcnt(0) lgkmcnt(0)
	v_add_u32_e32 v48, v32, v47
	v_add_u32_e32 v48, v48, v33
	v_add_u32_e32 v48, v48, v34
	v_add_u32_e32 v48, v48, v35
	v_add_u32_e32 v48, v48, v36
	v_add_u32_e32 v48, v48, v37
	v_add_u32_e32 v48, v48, v38
	v_add_u32_e32 v48, v48, v39
	v_add_u32_e32 v48, v48, v40
	v_add_u32_e32 v48, v48, v41
	v_add_u32_e32 v48, v48, v42
	v_add_u32_e32 v48, v48, v43
	v_add_u32_e32 v48, v48, v44
	v_add_u32_e32 v48, v48, v45
	v_add_u32_e32 v48, v48, v46
	v_cmp_ne_u32_e32 vcc, s22, v48
	s_and_saveexec_b64 s[2:3], vcc
	s_cbranch_execz .LBB0_165
	s_and_b32 s16, s23, 0xff
	s_mov_b64 s[14:15], -1
	s_cmp_eq_u32 s16, 0
	s_mov_b64 s[18:19], -1
	s_mov_b64 s[16:17], -1
	s_sleep 0
	s_cbranch_scc1 .LBB0_169
	s_and_saveexec_b64 s[20:21], s[18:19]
	s_cbranch_execz .LBB0_164
	s_branch .LBB0_172

.LBB0_180:
	s_and_b32 s18, s26, 0xff
	s_mov_b64 s[16:17], -1
	s_cmp_lg_u32 s18, 0
	s_mov_b64 s[18:19], -1
	s_sleep 0
	s_cbranch_scc1 .LBB0_184
	v_mov_b64_e32 v[2:3], s[6:7]
	flat_load_dword v0, v[2:3] sc1
	s_mov_b64 s[18:19], 0
	s_mov_b64 s[20:21], -1
	s_waitcnt vmcnt(0) lgkmcnt(0)
	v_cmp_eq_u32_e32 vcc, 0, v0
	s_and_saveexec_b64 s[22:23], vcc
	s_cmp_lt_u32 s26, 0x40001
	s_cselect_b64 s[18:19], -1, 0
	s_xor_b64 s[20:21], exec, -1
	s_and_b64 s[18:19], s[18:19], exec
	s_or_b64 exec, exec, s[22:23]

.LBB0_194:
	s_and_b32 s14, s22, 0xff
	s_cmp_lg_u32 s14, 0
	s_mov_b64 s[16:17], -1
	s_sleep 0
	s_cbranch_scc0 .LBB0_196
	s_mov_b64 s[18:19], -1
	s_and_saveexec_b64 s[20:21], s[16:17]
	s_cbranch_execz .LBB0_193
	s_branch .LBB0_199

.LBB0_218:
	v_mov_b64_e32 v[2:3], s[4:5]
	flat_load_dword v0, v[2:3] sc1
	v_mov_b64_e32 v[2:3], s[6:7]
	flat_load_dword v2, v[2:3] sc1
	v_mov_b64_e32 v[4:5], s[8:9]
	flat_load_dword v3, v[4:5] sc1
	v_mov_b64_e32 v[4:5], s[10:11]
	flat_load_dword v4, v[4:5] sc1
	v_readlane_b32 s3, v253, 2
	s_or_b64 s[74:75], s[74:75], exec
	s_or_b64 s[72:73], s[72:73], exec
	s_waitcnt vmcnt(0) lgkmcnt(0)
	v_add_u32_e32 v6, v2, v0
	v_add_u32_e32 v6, v6, v3
	v_add_u32_e32 v8, v6, v4
	v_mov_b64_e32 v[6:7], s[12:13]
	flat_load_dword v5, v[6:7] sc1
	v_mov_b64_e32 v[6:7], s[14:15]
	flat_load_dword v6, v[6:7] sc1
	s_waitcnt vmcnt(0) lgkmcnt(0)
	v_add_u32_e32 v8, v8, v5
	v_add_u32_e32 v10, v8, v6
	v_mov_b64_e32 v[8:9], s[16:17]
	flat_load_dword v7, v[8:9] sc1
	v_mov_b64_e32 v[8:9], s[18:19]
	flat_load_dword v8, v[8:9] sc1
	s_waitcnt vmcnt(0) lgkmcnt(0)
	v_add_u32_e32 v10, v10, v7
	v_add_u32_e32 v12, v10, v8
	v_mov_b64_e32 v[10:11], s[20:21]
	flat_load_dword v9, v[10:11] sc1
	v_mov_b64_e32 v[10:11], s[22:23]
	flat_load_dword v10, v[10:11] sc1
	s_waitcnt vmcnt(0) lgkmcnt(0)
	v_add_u32_e32 v12, v12, v9
	v_add_u32_e32 v14, v12, v10
	v_mov_b64_e32 v[12:13], s[24:25]
	flat_load_dword v11, v[12:13] sc1
	v_mov_b64_e32 v[12:13], s[26:27]
	flat_load_dword v12, v[12:13] sc1
	s_waitcnt vmcnt(0) lgkmcnt(0)
	v_add_u32_e32 v14, v14, v11
	v_add_u32_e32 v16, v14, v12
	v_mov_b64_e32 v[14:15], s[28:29]
	flat_load_dword v13, v[14:15] sc1
	v_mov_b64_e32 v[14:15], s[30:31]
	flat_load_dword v14, v[14:15] sc1
	s_waitcnt vmcnt(0) lgkmcnt(0)
	v_add_u32_e32 v16, v16, v13
	v_add_u32_e32 v18, v16, v14
	v_mov_b64_e32 v[16:17], s[40:41]
	flat_load_dword v15, v[16:17] sc1
	v_mov_b64_e32 v[16:17], s[44:45]
	flat_load_dword v16, v[16:17] sc1
	s_waitcnt vmcnt(0) lgkmcnt(0)
	v_add_u32_e32 v18, v18, v15
	v_add_u32_e32 v17, v18, v16
	v_cmp_ne_u32_e32 vcc, s3, v17
	s_and_saveexec_b64 s[46:47], vcc
	s_cbranch_execz .LBB0_217
	s_and_b32 s3, s94, 0xff
	s_mov_b64 s[56:57], -1
	s_cmp_eq_u32 s3, 0
	s_mov_b64 s[78:79], -1
	s_mov_b64 s[58:59], -1
	s_sleep 0
	s_cbranch_scc1 .LBB0_221
	s_and_saveexec_b64 s[82:83], s[78:79]
	s_cbranch_execz .LBB0_216
	s_branch .LBB0_224

.LBB0_232:
	s_and_b32 s3, s25, 0xff
	s_mov_b64 s[16:17], -1
	s_cmp_lg_u32 s3, 0
	s_mov_b64 s[18:19], -1
	s_sleep 0
	s_cbranch_scc1 .LBB0_236
	v_mov_b64_e32 v[4:5], s[8:9]
	flat_load_dword v0, v[4:5] sc1
	s_mov_b64 s[18:19], 0
	s_mov_b64 s[20:21], -1
	s_waitcnt vmcnt(0) lgkmcnt(0)
	v_cmp_eq_u32_e32 vcc, 0, v0
	s_and_saveexec_b64 s[22:23], vcc
	s_cmp_lt_u32 s25, 0x40001
	s_cselect_b64 s[18:19], -1, 0
	s_xor_b64 s[20:21], exec, -1
	s_and_b64 s[18:19], s[18:19], exec
	s_or_b64 exec, exec, s[22:23]

.LBB0_246:
	s_and_b32 s3, s22, 0xff
	s_mov_b64 s[14:15], -1
	s_cmp_lg_u32 s3, 0
	s_mov_b64 s[18:19], -1
	s_sleep 0
	s_cbranch_scc0 .LBB0_248
	s_and_saveexec_b64 s[20:21], s[18:19]
	s_cbranch_execz .LBB0_245
	s_branch .LBB0_251

.LBB0_591:
	v_mov_b64_e32 v[2:3], s[6:7]
	flat_load_dword v0, v[2:3] sc1
	v_mov_b64_e32 v[2:3], s[8:9]
	flat_load_dword v2, v[2:3] sc1
	v_mov_b64_e32 v[4:5], s[10:11]
	flat_load_dword v3, v[4:5] sc1
	v_mov_b64_e32 v[4:5], s[12:13]
	flat_load_dword v4, v[4:5] sc1
	v_readlane_b32 s3, v253, 2
	s_or_b64 s[74:75], s[74:75], exec
	s_or_b64 s[72:73], s[72:73], exec
	s_waitcnt vmcnt(0) lgkmcnt(0)
	v_add_u32_e32 v6, v2, v0
	v_add_u32_e32 v6, v6, v3
	v_add_u32_e32 v8, v6, v4
	v_mov_b64_e32 v[6:7], s[14:15]
	flat_load_dword v5, v[6:7] sc1
	v_mov_b64_e32 v[6:7], s[16:17]
	flat_load_dword v6, v[6:7] sc1
	s_waitcnt vmcnt(0) lgkmcnt(0)
	v_add_u32_e32 v8, v8, v5
	v_add_u32_e32 v10, v8, v6
	v_mov_b64_e32 v[8:9], s[18:19]
	flat_load_dword v7, v[8:9] sc1
	v_mov_b64_e32 v[8:9], s[20:21]
	flat_load_dword v8, v[8:9] sc1
	s_waitcnt vmcnt(0) lgkmcnt(0)
	v_add_u32_e32 v10, v10, v7
	v_add_u32_e32 v12, v10, v8
	v_mov_b64_e32 v[10:11], s[22:23]
	flat_load_dword v9, v[10:11] sc1
	v_mov_b64_e32 v[10:11], s[24:25]
	flat_load_dword v10, v[10:11] sc1
	s_waitcnt vmcnt(0) lgkmcnt(0)
	v_add_u32_e32 v12, v12, v9
	v_add_u32_e32 v14, v12, v10
	v_mov_b64_e32 v[12:13], s[26:27]
	flat_load_dword v11, v[12:13] sc1
	v_mov_b64_e32 v[12:13], s[28:29]
	flat_load_dword v12, v[12:13] sc1
	s_waitcnt vmcnt(0) lgkmcnt(0)
	v_add_u32_e32 v14, v14, v11
	v_add_u32_e32 v16, v14, v12
	v_mov_b64_e32 v[14:15], s[30:31]
	flat_load_dword v13, v[14:15] sc1
	v_mov_b64_e32 v[14:15], s[34:35]
	flat_load_dword v14, v[14:15] sc1
	s_waitcnt vmcnt(0) lgkmcnt(0)
	v_add_u32_e32 v16, v16, v13
	v_add_u32_e32 v18, v16, v14
	v_mov_b64_e32 v[16:17], s[40:41]
	flat_load_dword v15, v[16:17] sc1
	v_mov_b64_e32 v[16:17], s[44:45]
	flat_load_dword v16, v[16:17] sc1
	s_waitcnt vmcnt(0) lgkmcnt(0)
	v_add_u32_e32 v18, v18, v15
	v_add_u32_e32 v17, v18, v16
	v_cmp_ne_u32_e32 vcc, s3, v17
	s_and_saveexec_b64 s[46:47], vcc
	s_cbranch_execz .LBB0_590
	s_and_b32 s3, s94, 0xff
	s_mov_b64 s[56:57], -1
	s_cmp_eq_u32 s3, 0
	s_mov_b64 s[78:79], -1
	s_mov_b64 s[58:59], -1
	s_sleep 0
	s_cbranch_scc1 .LBB0_594
	s_and_saveexec_b64 s[82:83], s[78:79]
	s_cbranch_execz .LBB0_589
	s_branch .LBB0_597

.LBB0_605:
	s_and_b32 s3, s27, 0xff
	s_mov_b64 s[18:19], -1
	s_cmp_lg_u32 s3, 0
	s_mov_b64 s[20:21], -1
	s_sleep 0
	s_cbranch_scc1 .LBB0_609
	v_mov_b64_e32 v[4:5], s[10:11]
	flat_load_dword v0, v[4:5] sc1
	s_mov_b64 s[20:21], 0
	s_mov_b64 s[22:23], -1
	s_waitcnt vmcnt(0) lgkmcnt(0)
	v_cmp_eq_u32_e32 vcc, 0, v0
	s_and_saveexec_b64 s[24:25], vcc
	s_cmp_lt_u32 s27, 0x40001
	s_cselect_b64 s[20:21], -1, 0
	s_xor_b64 s[22:23], exec, -1
	s_and_b64 s[20:21], s[20:21], exec
	s_or_b64 exec, exec, s[24:25]

.LBB0_907:
	v_mov_b64_e32 v[2:3], s[6:7]
	flat_load_dword v0, v[2:3] sc1
	v_mov_b64_e32 v[2:3], s[8:9]
	flat_load_dword v2, v[2:3] sc1
	v_mov_b64_e32 v[4:5], s[10:11]
	flat_load_dword v3, v[4:5] sc1
	v_mov_b64_e32 v[4:5], s[12:13]
	flat_load_dword v4, v[4:5] sc1
	v_readlane_b32 s3, v253, 2
	s_or_b64 s[74:75], s[74:75], exec
	s_or_b64 s[72:73], s[72:73], exec
	s_waitcnt vmcnt(0) lgkmcnt(0)
	v_add_u32_e32 v6, v2, v0
	v_add_u32_e32 v6, v6, v3
	v_add_u32_e32 v8, v6, v4
	v_mov_b64_e32 v[6:7], s[14:15]
	flat_load_dword v5, v[6:7] sc1
	v_mov_b64_e32 v[6:7], s[16:17]
	flat_load_dword v6, v[6:7] sc1
	s_waitcnt vmcnt(0) lgkmcnt(0)
	v_add_u32_e32 v8, v8, v5
	v_add_u32_e32 v10, v8, v6
	v_mov_b64_e32 v[8:9], s[18:19]
	flat_load_dword v7, v[8:9] sc1
	v_mov_b64_e32 v[8:9], s[20:21]
	flat_load_dword v8, v[8:9] sc1
	s_waitcnt vmcnt(0) lgkmcnt(0)
	v_add_u32_e32 v10, v10, v7
	v_add_u32_e32 v12, v10, v8
	v_mov_b64_e32 v[10:11], s[22:23]
	flat_load_dword v9, v[10:11] sc1
	v_mov_b64_e32 v[10:11], s[24:25]
	flat_load_dword v10, v[10:11] sc1
	s_waitcnt vmcnt(0) lgkmcnt(0)
	v_add_u32_e32 v12, v12, v9
	v_add_u32_e32 v14, v12, v10
	v_mov_b64_e32 v[12:13], s[26:27]
	flat_load_dword v11, v[12:13] sc1
	v_mov_b64_e32 v[12:13], s[28:29]
	flat_load_dword v12, v[12:13] sc1
	s_waitcnt vmcnt(0) lgkmcnt(0)
	v_add_u32_e32 v14, v14, v11
	v_add_u32_e32 v16, v14, v12
	v_mov_b64_e32 v[14:15], s[30:31]
	flat_load_dword v13, v[14:15] sc1
	v_mov_b64_e32 v[14:15], s[34:35]
	flat_load_dword v14, v[14:15] sc1
	s_waitcnt vmcnt(0) lgkmcnt(0)
	v_add_u32_e32 v16, v16, v13
	v_add_u32_e32 v18, v16, v14
	v_mov_b64_e32 v[16:17], s[40:41]
	flat_load_dword v15, v[16:17] sc1
	v_mov_b64_e32 v[16:17], s[44:45]
	flat_load_dword v16, v[16:17] sc1
	s_waitcnt vmcnt(0) lgkmcnt(0)
	v_add_u32_e32 v18, v18, v15
	v_add_u32_e32 v17, v18, v16
	v_cmp_ne_u32_e32 vcc, s3, v17
	s_and_saveexec_b64 s[46:47], vcc
	s_cbranch_execz .LBB0_906
	s_and_b32 s3, s97, 0xff
	s_mov_b64 s[56:57], -1
	s_cmp_eq_u32 s3, 0
	s_mov_b64 s[78:79], -1
	s_mov_b64 s[58:59], -1
	s_sleep 0
	s_cbranch_scc1 .LBB0_910
	s_and_saveexec_b64 s[92:93], s[78:79]
	s_cbranch_execz .LBB0_905
	s_branch .LBB0_913

.LBB0_935:
	s_and_b32 s3, s24, 0xff
	s_mov_b64 s[16:17], -1
	s_cmp_lg_u32 s3, 0
	s_mov_b64 s[20:21], -1
	s_sleep 0
	s_cbranch_scc0 .LBB0_937
	s_and_saveexec_b64 s[22:23], s[20:21]
	s_cbranch_execz .LBB0_934
	s_branch .LBB0_940

.LBB0_971:
	v_mov_b64_e32 v[2:3], s[4:5]
	flat_load_dword v0, v[2:3] sc1
	v_mov_b64_e32 v[2:3], s[6:7]
	flat_load_dword v2, v[2:3] sc1
	v_mov_b64_e32 v[4:5], s[8:9]
	flat_load_dword v3, v[4:5] sc1
	v_mov_b64_e32 v[4:5], s[10:11]
	flat_load_dword v4, v[4:5] sc1
	v_readlane_b32 s3, v253, 2
	s_or_b64 s[74:75], s[74:75], exec
	s_or_b64 s[72:73], s[72:73], exec
	s_waitcnt vmcnt(0) lgkmcnt(0)
	v_add_u32_e32 v6, v2, v0
	v_add_u32_e32 v6, v6, v3
	v_add_u32_e32 v8, v6, v4
	v_mov_b64_e32 v[6:7], s[12:13]
	flat_load_dword v5, v[6:7] sc1
	v_mov_b64_e32 v[6:7], s[14:15]
	flat_load_dword v6, v[6:7] sc1
	s_waitcnt vmcnt(0) lgkmcnt(0)
	v_add_u32_e32 v8, v8, v5
	v_add_u32_e32 v10, v8, v6
	v_mov_b64_e32 v[8:9], s[16:17]
	flat_load_dword v7, v[8:9] sc1
	v_mov_b64_e32 v[8:9], s[18:19]
	flat_load_dword v8, v[8:9] sc1
	s_waitcnt vmcnt(0) lgkmcnt(0)
	v_add_u32_e32 v10, v10, v7
	v_add_u32_e32 v12, v10, v8
	v_mov_b64_e32 v[10:11], s[20:21]
	flat_load_dword v9, v[10:11] sc1
	v_mov_b64_e32 v[10:11], s[22:23]
	flat_load_dword v10, v[10:11] sc1
	s_waitcnt vmcnt(0) lgkmcnt(0)
	v_add_u32_e32 v12, v12, v9
	v_add_u32_e32 v14, v12, v10
	v_mov_b64_e32 v[12:13], s[24:25]
	flat_load_dword v11, v[12:13] sc1
	v_mov_b64_e32 v[12:13], s[26:27]
	flat_load_dword v12, v[12:13] sc1
	s_waitcnt vmcnt(0) lgkmcnt(0)
	v_add_u32_e32 v14, v14, v11
	v_add_u32_e32 v16, v14, v12
	v_mov_b64_e32 v[14:15], s[28:29]
	flat_load_dword v13, v[14:15] sc1
	v_mov_b64_e32 v[14:15], s[30:31]
	flat_load_dword v14, v[14:15] sc1
	s_waitcnt vmcnt(0) lgkmcnt(0)
	v_add_u32_e32 v16, v16, v13
	v_add_u32_e32 v18, v16, v14
	v_mov_b64_e32 v[16:17], s[40:41]
	flat_load_dword v15, v[16:17] sc1
	v_mov_b64_e32 v[16:17], s[44:45]
	flat_load_dword v16, v[16:17] sc1
	s_waitcnt vmcnt(0) lgkmcnt(0)
	v_add_u32_e32 v18, v18, v15
	v_add_u32_e32 v17, v18, v16
	v_cmp_ne_u32_e32 vcc, s3, v17
	s_and_saveexec_b64 s[46:47], vcc
	s_cbranch_execz .LBB0_970
	s_and_b32 s3, s94, 0xff
	s_mov_b64 s[56:57], -1
	s_cmp_eq_u32 s3, 0
	s_mov_b64 s[78:79], -1
	s_mov_b64 s[58:59], -1
	s_sleep 0
	s_cbranch_scc1 .LBB0_974
	s_and_saveexec_b64 s[92:93], s[78:79]
	s_cbranch_execz .LBB0_969
	s_branch .LBB0_977

.LBB0_985:
	s_and_b32 s3, s26, 0xff
	s_mov_b64 s[16:17], -1
	s_cmp_lg_u32 s3, 0
	s_mov_b64 s[18:19], -1
	s_sleep 0
	s_cbranch_scc1 .LBB0_989
	v_mov_b64_e32 v[4:5], s[8:9]
	flat_load_dword v0, v[4:5] sc1
	s_mov_b64 s[18:19], 0
	s_mov_b64 s[20:21], -1
	s_waitcnt vmcnt(0) lgkmcnt(0)
	v_cmp_eq_u32_e32 vcc, 0, v0
	s_and_saveexec_b64 s[22:23], vcc
	s_cmp_lt_u32 s26, 0x40001
	s_cselect_b64 s[18:19], -1, 0
	s_xor_b64 s[20:21], exec, -1
	s_and_b64 s[18:19], s[18:19], exec
	s_or_b64 exec, exec, s[22:23]
